# GLA scan chunk loop: all LDS reads issued up front with counted lgkmcnt, cvt_pk for state, two o-tile chains interleaved
# baseline (speedup 1.0000x reference)
; __global__ void __launch_bounds__(NWAVES * 64, 2) mega_fwd(Args A) {
;     ...
;     for (int step = 0; step < 3 * DEPTH; ++step) {
;         const int l = step / 3, kind = step - 3 * l;
;         unsigned char* wl = ws + WS_W + (size_t)l * LW_END;
;         const unsigned long long* ssq = (const unsigned long long*)(ws + WS_CTL + CTL_SSQ) + (size_t)step * NTOK; unsigned long long* ssq_next = (unsigned long long*)(ws + WS_CTL + CTL_SSQ) + (size_t)(step + 1) * NTOK;
;         if (kind != 1) {
;             { pg8::Gemm g{H, (const bf16*)(wl + (kind == 0 ? LW_WI1 : LW_WI2)), NTOK, NWI, DM}; pg8::StaticOrder S; S.init(NTOK, NWI, G, bx);
;               pg8::EpiSwiglu E{ACT, DFF, ssq};
;               pg8::gemm_phase<pg8::EpiSwiglu, pg8::StaticOrder, true, true>(lds + RING_OFF, g, S, E); }
;             { const int rem1 = ((NTOK / 256) * (NWI / 256)) % G;
;               conv_until(A, lds, l * TL_LAYER + (kind == 0 ? TL_WIN : TL_LAYER), (rem1 != 0 && bx >= rem1) ? 3 : 0); }
;             xcd_barrier(bar);
;         } else {
;             const bool std256 = (G == 256);
;             unsigned char* XB8 = ws + WS_X;
; #pragma unroll 1
;             for (int part = 0; part < 3; ++part) {
;                 bool do16, do8; int i16, n16, g8, c8, i8, n8;
;                 if (std256) { do16 = part == 0 || (part == 1 && bx < 64); i16 = part ? 2 : 0; n16 = part ? 1 : 2;
;                               do8 = (part == 1 && bx >= 64) || (part == 2 && bx < 128); g8 = part == 1 ? 192 : 128; c8 = part == 1 ? bx - 64 : bx; i8 = part == 1 ? 0 : 3; n8 = part == 1 ? 2 : 3; }
;                 else { do16 = part == 0; i16 = 0; n16 = 1 << 20; do8 = part == 1; g8 = G; c8 = bx; i8 = 0; n8 = 1 << 20; }
;                 if (do16) { pg8::Gemm g{H, (const bf16*)(wl + LW_WIN), NTOK, C_GATE, DM}; pg8::RangeOrder S; S.init(NTOK, C_GATE, G, bx); S.i0 = i16; S.n = n16;
;                     pg8::EpiProj E{PROJ, NPROJ, (const float*)A.in[7] + (size_t)l * 6144, 1 << 20, ssq, 1.0f};
;                     pg8::gemm_phase<pg8::EpiProj, pg8::RangeOrder, true, true>(lds + RING_OFF, g, S, E); }
;                 if (do8) { pg8::Gemm g{(const bf16*)XB8, (const bf16*)(wl + LW_WIN + WIN8_OFF), NTOK, 6144, DM / 2}; pg8::RangeOrder S; S.init(NTOK, 6144, g8, c8); S.i0 = i8; S.n = n8;
.LBB0_284:
	v_writelane_b32 v252, s64, 42
	s_nop 1
	v_writelane_b32 v252, s65, 43
	v_writelane_b32 v252, s66, 44
	v_writelane_b32 v252, s67, 45
	v_writelane_b32 v252, s68, 46
	v_writelane_b32 v252, s69, 47
	v_writelane_b32 v252, s70, 48
	v_writelane_b32 v252, s71, 49
	v_writelane_b32 v252, s72, 50
	v_writelane_b32 v252, s73, 51
	v_writelane_b32 v252, s74, 52
	v_writelane_b32 v252, s75, 53
	v_writelane_b32 v252, s76, 54
	v_writelane_b32 v252, s77, 55
	v_writelane_b32 v252, s78, 56
	v_writelane_b32 v252, s79, 57
	s_or_b64 exec, exec, s[0:1]
	s_cmpk_lg_i32 s95, 0x100
	s_cselect_b64 s[0:1], -1, 0
	s_and_b64 s[0:1], s[0:1], exec
	s_cselect_b32 s69, s95, 0x80
	s_add_i32 s4, s97, 0xffffff80
	s_cmpk_lg_i32 s95, 0x100
	s_cselect_b64 s[0:1], -1, 0
	s_and_b64 s[2:3], s[0:1], exec
	s_cselect_b32 s20, s97, s4
	v_readlane_b32 s4, v252, 2
	v_readlane_b32 s18, v252, 16
	v_readlane_b32 s19, v252, 17
	s_add_u32 s74, s18, 0x10000
	s_addc_u32 s2, s19, 0
	v_readlane_b32 s5, v252, 3
	v_readlane_b32 s6, v252, 4
	v_readlane_b32 s7, v252, 5
	v_readlane_b32 s8, v252, 6
	v_readlane_b32 s9, v252, 7
	v_readlane_b32 s10, v252, 8
	v_readlane_b32 s11, v252, 9
	v_readlane_b32 s12, v252, 10
	v_readlane_b32 s13, v252, 11
	v_readlane_b32 s14, v252, 12
	v_readlane_b32 s15, v252, 13
	v_readlane_b32 s16, v252, 14
	v_readlane_b32 s17, v252, 15
	v_writelane_b32 v252, s2, 58
	s_add_u32 s2, s18, 0x35e00000
	s_addc_u32 s3, s19, 0
	s_add_u32 s88, s18, 0x3b600000
	s_addc_u32 s89, s19, 0
	v_writelane_b32 v252, s2, 59
	s_add_u32 s12, s18, 0x45e00000
	s_addc_u32 s13, s19, 0
	v_writelane_b32 v252, s3, 60
	v_writelane_b32 v252, s12, 61
	s_add_u32 s2, s18, 0x4c200000
	v_writelane_b32 v252, s13, 62
	s_addc_u32 s3, s19, 0
	v_writelane_b32 v252, s2, 63
	s_waitcnt vmcnt(15)
	v_mov_b32_e32 v3, 0
	v_mov_b32_e32 v216, 1
	v_writelane_b32 v253, s3, 0
	s_add_u32 s2, s18, 0x4e200000
	s_addc_u32 s3, s19, 0
	v_writelane_b32 v253, s2, 1
	v_mov_b32_e32 v217, 0x7f7f7f7f
	v_mov_b32_e32 v225, 0x43e00000
	v_writelane_b32 v253, s3, 2
	s_add_u32 s2, s18, 0x4fa00000
	s_addc_u32 s3, s19, 0
	v_writelane_b32 v253, s2, 3
	v_mov_b64_e32 v[226:227], 0x2ff
	v_mov_b32_e32 v222, 0x41b17218
	v_writelane_b32 v253, s3, 4
	s_add_u32 s2, s18, 0x4fb00000
	s_addc_u32 s3, s19, 0
	v_writelane_b32 v253, s2, 5
	v_mbcnt_hi_u32_b32 v223, -1, v76
	v_mov_b32_e32 v224, 0xf149f2ca
	v_writelane_b32 v253, s3, 6
	s_add_u32 s2, s18, 0x200000
	v_writelane_b32 v253, s2, 7
	s_addc_u32 s2, s19, 0
	s_cmpk_lt_i32 s97, 0x580
	v_writelane_b32 v253, s2, 8
	s_cselect_b64 s[2:3], -1, 0
	v_writelane_b32 v253, s2, 9
	s_ashr_i32 s21, s97, 31
	s_movk_i32 s75, 0xc0
	v_writelane_b32 v253, s3, 10
	s_lshr_b32 s2, s21, 29
	s_add_i32 s3, s97, s2
	s_ashr_i32 s2, s3, 3
	s_and_b32 s3, s3, -8
	s_sub_i32 s5, s97, s3
	s_ashr_i32 s3, s95, 31
	s_add_u32 s6, s18, 0x4200
	v_writelane_b32 v253, s3, 11
	s_addc_u32 s7, s19, 0
	v_writelane_b32 v253, s6, 12
	s_movk_i32 s76, 0x300
	s_movk_i32 s77, 0x5400
	v_writelane_b32 v253, s7, 13
	s_add_u32 s6, s18, 0x4400
	s_addc_u32 s7, s19, 0
	v_writelane_b32 v253, s6, 14
	s_movk_i32 s81, 0x7fff
	s_mov_b32 s82, 0xffff0000
	v_writelane_b32 v253, s7, 15
	s_add_u32 s6, s18, 0x4500
	s_addc_u32 s7, s19, 0
	v_writelane_b32 v253, s6, 16
	s_movk_i32 s61, 0x1110
	s_movk_i32 s84, 0x15ff
	v_writelane_b32 v253, s7, 17
	s_add_u32 s6, s18, 0x4600
	s_addc_u32 s7, s19, 0
	v_writelane_b32 v253, s6, 18
	s_mov_b32 s85, 0xc3e00000
	s_movk_i32 s33, 0xff
	v_writelane_b32 v253, s7, 19
	s_add_u32 s6, s18, 0x4700
	s_addc_u32 s7, s19, 0
	v_writelane_b32 v253, s6, 20
	s_movk_i32 s66, 0x90
	s_mov_b32 s96, 0x2aaaaaab
	v_writelane_b32 v253, s7, 21
	s_add_u32 s6, s18, 0x4800
	s_addc_u32 s7, s19, 0
	v_writelane_b32 v253, s6, 22
	s_movk_i32 s36, 0x190
	s_movk_i32 s37, 0xff40
	v_writelane_b32 v253, s7, 23
	s_add_u32 s6, s18, 0x4900
	s_addc_u32 s7, s19, 0
	v_writelane_b32 v253, s6, 24
	s_movk_i32 s38, 0x567
	s_movk_i32 s39, 0x1500
	v_writelane_b32 v253, s7, 25
	s_add_u32 s6, s18, 0x4a00
	s_addc_u32 s7, s19, 0
	v_writelane_b32 v253, s6, 26
	s_movk_i32 s56, 0x1800
	s_movk_i32 s57, 0xc80
	v_writelane_b32 v253, s7, 27
	s_add_u32 s6, s18, 0x4b00
	s_addc_u32 s7, s19, 0
	v_writelane_b32 v253, s6, 28
	s_movk_i32 s58, 0x3ff
	s_mov_b32 s80, 0xefa18f08
	v_writelane_b32 v253, s7, 29
	s_add_u32 s6, s18, 0x4c00
	s_addc_u32 s7, s19, 0
	v_writelane_b32 v253, s6, 30
	s_mov_b32 s62, 0
	s_mov_b32 s94, 0x3e000000
	v_writelane_b32 v253, s7, 31
	s_add_u32 s6, s18, 0x4d00
	s_addc_u32 s7, s19, 0
	v_writelane_b32 v253, s6, 32
	s_waitcnt lgkmcnt(0)
	s_barrier
; __global__ void __launch_bounds__(NWAVES * 64, 2) mega_fwd(Args A) {
;     ...
;             if (G > 96) { if (bx < 48) gla_scan_unit(lds, ws + WS_GPRE, GO, bx);
;                           else for (int u = bx - 48; u < 256; u += G - 48) att_unit(lds, PROJ, COS, SIN, (const float*)A.in[8] + l * 12, Y, u); }
;             else { for (int u = bx; u < 48; u += G) gla_scan_unit(lds, ws + WS_GPRE, GO, u);
;                    for (int u = bx; u < 256; u += G) att_unit(lds, PROJ, COS, SIN, (const float*)A.in[8] + l * 12, Y, u); }
;             conv_until(A, lds, l * TL_LAYER + TL_WI2, (G > 96 && bx >= 48) ? ((bx - 48) + (G - 48) < 256 ? 1 : 3) : 0);
;             xcd_barrier(bar);
;             { int t_ = threadIdx.x; asm volatile("" : "+v"(t_)); gla_norm_phase(GO, PROJ, (const float*)A.in[13] + l * 768, Y + (size_t)2 * NTOK * BRW, bx * NWAVES + __builtin_amdgcn_readfirstlane(t_ >> 6), G * NWAVES, t_ & 63); }
	v_writelane_b32 v253, s7, 33
	s_add_u32 s6, s18, 0x4e00
	s_addc_u32 s7, s19, 0
	v_writelane_b32 v253, s6, 34
	s_nop 1
	v_writelane_b32 v253, s7, 35
	s_add_u32 s6, s18, 0x4f00
	s_addc_u32 s7, s19, 0
	v_writelane_b32 v253, s6, 36
	s_nop 1
	v_writelane_b32 v253, s7, 37
	s_add_u32 s6, s18, 0x5000
	s_addc_u32 s7, s19, 0
	v_writelane_b32 v253, s6, 38
	s_nop 1
	v_writelane_b32 v253, s7, 39
	s_add_u32 s6, s18, 0x5100
	s_addc_u32 s7, s19, 0
	v_writelane_b32 v253, s6, 40
	s_nop 1
	v_writelane_b32 v253, s7, 41
	s_add_u32 s6, s18, 0x5200
	s_addc_u32 s7, s19, 0
	v_writelane_b32 v253, s6, 42
	s_nop 1
	v_writelane_b32 v253, s7, 43
	s_add_u32 s6, s18, 0x5300
	s_addc_u32 s7, s19, 0
	v_writelane_b32 v253, s6, 44
	s_nop 1
	v_writelane_b32 v253, s7, 45
	s_add_u32 s6, s18, 0x7400
	s_addc_u32 s7, s19, 0
	v_writelane_b32 v253, s6, 46
	s_nop 1
	v_writelane_b32 v253, s7, 47
	s_add_u32 s6, s18, 0x7500
	s_addc_u32 s7, s19, 0
	v_writelane_b32 v253, s6, 48
	s_cmpk_eq_i32 s95, 0x100
	s_nop 0
	v_writelane_b32 v253, s7, 49
	s_cselect_b64 s[6:7], -1, 0
	s_add_u32 s72, s18, 0x2fe00000
	s_addc_u32 s73, s19, 0
	v_writelane_b32 v253, s6, 50
	s_cmp_lt_i32 s97, 64
	s_nop 0
	v_writelane_b32 v253, s7, 51
	s_cselect_b64 s[6:7], -1, 0
	v_writelane_b32 v253, s6, 52
	s_cmp_gt_i32 s97, 63
	s_nop 0
	v_writelane_b32 v253, s7, 53
	s_cselect_b64 s[6:7], -1, 0
	v_writelane_b32 v253, s6, 54
	s_cmpk_lt_i32 s97, 0x80
	s_nop 0
	v_writelane_b32 v253, s7, 55
	s_cselect_b64 s[6:7], -1, 0
	v_writelane_b32 v253, s6, 56
	s_sub_i32 s3, s97, 64
	s_nop 0
	v_writelane_b32 v253, s7, 57
	s_add_u32 s6, s18, 0x3b602400
	v_writelane_b32 v253, s3, 58
	s_addc_u32 s7, s19, 0
	v_writelane_b32 v253, s6, 59
	s_cmpk_gt_i32 s97, 0x7f
	s_nop 0
	v_writelane_b32 v253, s7, 60
	s_cselect_b64 s[6:7], -1, 0
	s_or_b64 s[0:1], s[6:7], s[0:1]
	v_writelane_b32 v253, s0, 61
	s_nop 1
	v_writelane_b32 v253, s1, 62
	s_and_b32 s0, s69, 3
	s_cmp_lg_u32 s0, 0
	s_cselect_b64 s[0:1], -1, 0
	v_writelane_b32 v253, s0, 63
	s_cmpk_lt_i32 s20, 0x200
	s_nop 0
	v_writelane_b32 v254, s1, 0
	s_cselect_b64 s[0:1], -1, 0
	v_writelane_b32 v254, s0, 1
	s_nop 1
	v_writelane_b32 v254, s1, 2
	s_add_u32 s0, s18, 0x46a00000
	s_addc_u32 s1, s19, 0
	v_writelane_b32 v254, s0, 3
	s_and_b32 s4, s20, 3
	s_nop 0
	v_writelane_b32 v254, s1, 4
	s_mul_i32 s0, s4, 0x12000
	s_add_u32 s0, s34, s0
	v_writelane_b32 v254, s0, 5
	v_writelane_b32 v254, s34, 6
	s_addc_u32 s0, s35, 0
	s_lshl_b32 s68, 2, s4
	v_writelane_b32 v254, s35, 7
	v_writelane_b32 v254, s0, 8
	s_lshl_b32 s1, s20, 4
	s_lshl_b32 s0, s69, 4
	s_add_u32 s22, s18, 0x4fc00000
	v_writelane_b32 v254, s0, 9
	s_addc_u32 s23, s19, 0
	s_lshl_b32 s0, s20, 6
	s_and_b32 s0, s0, 0x7c0
	v_writelane_b32 v254, s1, 10
	s_and_b32 s1, s1, 0xfffff800
	s_or_b32 s0, s1, s0
	s_ashr_i32 s1, s0, 31
	v_writelane_b32 v254, s0, 11
	s_bfe_u32 s3, s20, 0x20005
	s_mov_b32 s35, 0
	v_writelane_b32 v254, s1, 12
	s_mul_i32 s0, s3, 0x60
	v_writelane_b32 v254, s20, 13
	s_add_i32 s1, s0, 0x920
	v_writelane_b32 v254, s1, 14
	v_writelane_b32 v254, s0, 15
	s_bitset1_b32 s0, 11
	s_cmpk_lt_i32 s95, 0x61
	v_writelane_b32 v254, s0, 16
	s_cselect_b64 s[0:1], -1, 0
	s_cmpk_gt_i32 s95, 0x60
	v_writelane_b32 v254, s0, 17
	s_cselect_b64 s[6:7], -1, 0
	s_cmp_lt_i32 s97, 48
	v_writelane_b32 v254, s1, 18
	s_cselect_b64 s[0:1], -1, 0
	v_writelane_b32 v254, s0, 19
	s_cmpk_lt_i32 s97, 0x100
	s_nop 0
	v_writelane_b32 v254, s1, 20
	s_cselect_b64 s[0:1], -1, 0
	v_writelane_b32 v254, s0, 21
	s_nop 1
	v_writelane_b32 v254, s1, 22
	s_sub_i32 s0, s97, 48
	v_writelane_b32 v254, s0, 23
	s_cmpk_lt_i32 s97, 0x130
	s_mul_hi_i32 s0, s97, 0x55555556
	s_cselect_b64 s[8:9], -1, 0
	s_lshr_b32 s1, s0, 31
	s_add_i32 s10, s0, s1
	s_mul_i32 s0, s10, -3
	s_add_i32 s0, s0, s97
	v_writelane_b32 v254, s8, 24
	s_lshl_b32 s1, s0, 13
	s_add_i32 s1, s1, 0x8000
	v_writelane_b32 v254, s9, 25
	v_writelane_b32 v254, s1, 26
	s_sub_i32 s1, s95, 48
	v_writelane_b32 v254, s1, 27
	s_lshl_b32 s8, s10, 5
	s_mul_i32 s1, s10, 0x1c4000
	v_writelane_b32 v254, s8, 28
	s_mul_hi_i32 s8, s8, 0xe200
	s_add_u32 s14, s22, s1
	s_addc_u32 s15, s23, s8
	s_add_u32 s8, s14, 0xe000
	v_writelane_b32 v254, s14, 29
	s_addc_u32 s9, s15, 0
	s_lshl_b32 s1, s10, 9
	s_lshl_b32 s0, s0, 6
	v_writelane_b32 v254, s15, 30
	s_and_b32 s11, s1, 0xfffff800
	s_ashr_i32 s1, s0, 31
	v_writelane_b32 v254, s8, 31
	s_cmp_gt_i32 s97, 47
	s_nop 0
	v_writelane_b32 v254, s9, 32
	s_cselect_b64 s[8:9], -1, 0
	v_writelane_b32 v254, s8, 33
	s_and_b64 s[14:15], s[8:9], s[6:7]
	s_add_i32 s6, s97, s95
	s_addk_i32 s6, 0xffa0
	v_writelane_b32 v254, s9, 34
	s_cmpk_lt_i32 s6, 0x100
	s_cselect_b32 s8, 3, 5
	v_writelane_b32 v254, s14, 35
	s_and_b64 s[6:7], s[14:15], exec
	s_cselect_b32 s6, s8, 0
	v_writelane_b32 v254, s15, 36
	v_writelane_b32 v254, s6, 37
	s_add_u32 s6, s18, 0x47600000
	v_writelane_b32 v254, s6, 38
	s_addc_u32 s6, s19, 0
	v_writelane_b32 v254, s6, 39
	s_lshl_b32 s14, s95, 5
	s_lshl_b32 s6, s5, 5
	s_cmp_lt_i32 s5, 0
	s_movk_i32 s7, 0xb1
; __global__ void __launch_bounds__(NWAVES * 64, 2) mega_fwd(Args A) {
;     ...
;             { const int rem1 = ((NTOK / 256) * (NWI / 256)) % G;
;               conv_until(A, lds, l * TL_LAYER + (kind == 0 ? TL_WIN : TL_LAYER), (rem1 != 0 && bx >= rem1) ? 3 : 0); }
;             xcd_barrier(bar);
;         } else {
;             const bool std256 = (G == 256);
;             unsigned char* XB8 = ws + WS_X;
; #pragma unroll 1
;             for (int part = 0; part < 3; ++part) {
;                 bool do16, do8; int i16, n16, g8, c8, i8, n8;
;                 if (std256) { do16 = part == 0 || (part == 1 && bx < 64); i16 = part ? 2 : 0; n16 = part ? 1 : 2;
;                               do8 = (part == 1 && bx >= 64) || (part == 2 && bx < 128); g8 = part == 1 ? 192 : 128; c8 = part == 1 ? bx - 64 : bx; i8 = part == 1 ? 0 : 3; n8 = part == 1 ? 2 : 3; }
;                 else { do16 = part == 0; i16 = 0; n16 = 1 << 20; do8 = part == 1; g8 = G; c8 = bx; i8 = 0; n8 = 1 << 20; }
;                 if (do16) { pg8::Gemm g{H, (const bf16*)(wl + LW_WIN), NTOK, C_GATE, DM}; pg8::RangeOrder S; S.init(NTOK, C_GATE, G, bx); S.i0 = i16; S.n = n16;
;                     pg8::EpiProj E{PROJ, NPROJ, (const float*)A.in[7] + (size_t)l * 6144, 1 << 20, ssq, 1.0f};
;                     pg8::gemm_phase<pg8::EpiProj, pg8::RangeOrder, true, true>(lds + RING_OFF, g, S, E); }
;                 if (do8) { pg8::Gemm g{(const bf16*)XB8, (const bf16*)(wl + LW_WIN + WIN8_OFF), NTOK, 6144, DM / 2}; pg8::RangeOrder S; S.init(NTOK, 6144, g8, c8); S.i0 = i8; S.n = n8;
;                     pg8::EpiGate8 E{(unsigned char*)(PROJ + C_GATE), NPROJ * 2, (const float*)A.in[7] + (size_t)l * 6144, ssq, 1.0f / 2048.0f};
;                     pg8::gemm_phase<pg8::EpiGate8, pg8::RangeOrder, true, true, true>(lds + RING_OFF, g, S, E); }
;                 if (part == 1) xcd_barrier(bar);
;                 if (part == 2 && (!std256 || bx >= 128)) { const int mb = std256 ? bx - 128 : bx, ms = std256 ? 128 : G;
;                     if ((ms & 3) == 0) pool_units(lds, PROJ, (const bf16*)(ws + WS_WPT) + (size_t)l * 4 * 192 * 192, Y + (size_t)NTOK * BRW, mb, ms, 512);
;                     else for (int u = mb; u < 512; u += ms) pool_units(lds, PROJ, (const bf16*)(ws + WS_WPT) + (size_t)l * 4 * 192 * 192, Y + (size_t)NTOK * BRW, u, 512, 512);
	s_cselect_b32 s7, s7, 0xb0
	s_mul_i32 s7, s5, s7
	s_mul_i32 s5, s5, 33
	s_cselect_b32 s5, s5, s6
	s_add_i32 s7, s7, s2
	s_mul_hi_i32 s6, s7, 0x2e8ba2e9
	s_lshr_b32 s8, s6, 31
	s_ashr_i32 s6, s6, 6
	s_add_i32 s6, s6, s8
	s_mul_i32 s8, s6, 0x160
	s_sub_i32 s7, s7, s8
	s_bfe_u32 s8, s7, 0x3001c
	s_add_i32 s8, s7, s8
	s_and_b32 s9, s8, 0xfff8
	s_sub_i32 s7, s7, s9
	s_lshl_b32 s6, s6, 3
	s_sext_i32_i16 s8, s8
	s_sext_i32_i16 s7, s7
	s_add_i32 s16, s6, s7
	s_ashr_i32 s6, s8, 3
	v_writelane_b32 v254, s6, 40
	s_lshr_b32 s6, s8, 3
	s_bfe_i64 s[6:7], s[6:7], 0x100000
	s_lshl_b64 s[6:7], s[6:7], 20
	v_writelane_b32 v254, s6, 41
	s_ashr_i32 s17, s16, 31
	s_nop 0
	v_writelane_b32 v254, s7, 42
	s_mov_b32 s6, s16
	v_writelane_b32 v254, s6, 43
	s_nop 1
	v_writelane_b32 v254, s7, 44
	s_lshl_b64 s[6:7], s[16:17], 20
	s_add_u32 s6, s90, s6
	s_addc_u32 s7, s91, s7
	s_add_u32 s8, s6, 0x80000
	s_addc_u32 s9, s7, 0
	v_writelane_b32 v254, s8, 45
	s_nop 1
	v_writelane_b32 v254, s9, 46
	s_add_u32 s8, s6, 0x2000
	v_writelane_b32 v254, s6, 47
	s_addc_u32 s9, s7, 0
	s_add_i32 s2, s5, s2
	s_ashr_i32 s5, s2, 31
	s_lshr_b32 s5, s5, 26
	s_add_i32 s5, s2, s5
	v_writelane_b32 v254, s7, 48
	s_and_b32 s6, s5, 0xffc0
	s_sub_i32 s2, s2, s6
	s_bfe_i32 s6, s2, 0x80000
	s_bfe_u32 s6, s6, 0x3000c
	s_add_i32 s6, s2, s6
	s_and_b32 s7, s6, 0xf8
	s_sub_i32 s2, s2, s7
	s_ashr_i32 s5, s5, 6
	s_lshl_b32 s5, s5, 3
	s_sext_i32_i8 s2, s2
	s_add_i32 s5, s5, s2
	s_bfe_i32 s2, s6, 0x80000
	v_writelane_b32 v254, s8, 49
	s_sext_i32_i16 s2, s2
	s_ashr_i32 s6, s2, 3
	v_writelane_b32 v254, s9, 50
	s_lshr_b32 s2, s2, 3
	v_writelane_b32 v254, s6, 51
	s_bfe_i64 s[6:7], s[2:3], 0x100000
	v_writelane_b32 v254, s6, 52
	s_mul_hi_i32 s2, s5, 0x60000
	s_nop 0
	v_writelane_b32 v254, s7, 53
	v_writelane_b32 v254, s5, 54
	s_mul_i32 s5, s5, 0x60000
	s_add_u32 s6, s12, s5
	s_addc_u32 s7, s13, s2
	s_add_u32 s8, s6, 0x30000
	s_addc_u32 s9, s7, 0
	v_writelane_b32 v254, s8, 55
	s_nop 1
	v_writelane_b32 v254, s9, 56
	s_add_u32 s8, s6, 0x2000
	v_writelane_b32 v254, s6, 57
	s_addc_u32 s9, s7, 0
	s_abs_i32 s2, s95
	v_cvt_f32_u32_e32 v1, s2
	v_writelane_b32 v254, s7, 58
	s_sub_i32 s5, 0, s2
	v_writelane_b32 v254, s8, 59
	v_rcp_iflag_f32_e32 v1, v1
	s_nop 0
	v_writelane_b32 v254, s9, 60
	v_mul_f32_e32 v1, 0x4f7ffffe, v1
	v_cvt_u32_f32_e32 v1, v1
	s_nop 0
	v_readfirstlane_b32 s6, v1
	s_mul_i32 s5, s5, s6
	s_mul_hi_u32 s5, s6, s5
	s_add_i32 s6, s6, s5
	s_mul_hi_u32 s5, s6, 0x580
	s_mul_i32 s5, s5, s2
	s_sub_i32 s5, 0x580, s5
	s_sub_i32 s6, s5, s2
	s_cmp_ge_u32 s5, s2
	s_cselect_b32 s5, s6, s5
	s_sub_i32 s6, s5, s2
	s_cmp_ge_u32 s5, s2
	s_cselect_b32 s2, s6, s5
	s_cmp_lg_u32 s2, 0
	s_cselect_b64 s[6:7], -1, 0
	s_cmp_ge_i32 s97, s2
	s_cselect_b64 s[8:9], -1, 0
	s_and_b64 s[6:7], s[6:7], s[8:9]
	s_mul_i32 s2, s4, 0xc0
	v_writelane_b32 v254, s6, 61
	s_and_b64 s[4:5], s[6:7], exec
	s_cselect_b32 s4, 3, 0
	v_writelane_b32 v254, s7, 62
	v_writelane_b32 v255, s2, 0
	s_lshl_b32 s2, s2, 1
	v_writelane_b32 v254, s4, 63
	s_add_u32 s4, s88, s2
	s_addc_u32 s5, s89, 0
	v_writelane_b32 v255, s4, 1
	s_and_b32 s2, s10, 3
	s_mulk_i32 s2, 0x300
	v_writelane_b32 v255, s5, 2
	s_mul_i32 s4, s11, 0xc00
	s_lshl_b32 s5, s97, 6
	s_or_b32 s2, s4, s2
	s_lshl_b64 s[0:1], s[0:1], 2
	v_writelane_b32 v255, s5, 3
	s_lshl_b32 s5, s95, 6
	s_mul_hi_i32 s4, s11, 0xc00
	s_add_u32 s0, s2, s0
	s_addc_u32 s1, s4, s1
	s_add_u32 s0, s18, s0
	v_writelane_b32 v255, s5, 4
	s_addc_u32 s1, s19, s1
	v_writelane_b32 v255, s0, 5
	s_mul_i32 s2, s95, 0x18000
	s_add_i32 s93, 0, 0x20180
	v_writelane_b32 v255, s1, 6
	s_mul_i32 s0, s3, 0xc0
	s_mul_hi_i32 s3, s14, 0xc00
	v_writelane_b32 v255, s2, 7
	s_lshl_b32 s1, s97, 9
	s_lshl_b32 s0, s0, 1
	v_writelane_b32 v255, s3, 8
	s_mul_i32 s2, s95, 0xa8000
	v_writelane_b32 v255, s14, 9
	s_mul_hi_i32 s3, s14, 0x5400
	v_writelane_b32 v255, s2, 10
	s_add_i32 s60, 0, 0x20184
	v_mov_b32_e32 v1, 0x358637bd
	v_writelane_b32 v255, s3, 11
	v_writelane_b32 v255, s1, 12
	s_lshl_b32 s1, s95, 11
	v_writelane_b32 v255, s1, 13
	s_lshl_b32 s1, s95, 4
	v_writelane_b32 v255, s1, 14
	s_lshl_b32 s1, s95, 10
	v_writelane_b32 v255, s1, 15
	s_lshl_b32 s1, s95, 9
	v_writelane_b32 v255, s1, 16
	s_add_i32 s1, 0, 0x20160
	v_writelane_b32 v255, s1, 17
	s_add_i32 s1, 0, 0x20164
	v_writelane_b32 v255, s1, 18
	s_add_i32 s1, 0, 0x2d00
	v_writelane_b32 v255, s1, 19
	v_writelane_b32 v255, s0, 20
	s_add_i32 s64, 0, 0x12600
	s_nop 0
	v_writelane_b32 v255, s1, 21
	s_add_i32 s0, 0, 0xf000
	v_writelane_b32 v255, s0, 22
	s_add_i32 s0, 0, 0x8800
	v_writelane_b32 v255, s0, 23
	v_writelane_b32 v255, s90, 24
	s_nop 1
	v_writelane_b32 v255, s91, 25
	v_writelane_b32 v255, s69, 26
	v_writelane_b32 v255, s88, 27
	s_nop 1
	v_writelane_b32 v255, s89, 28
	v_writelane_b32 v255, s21, 29
	v_writelane_b32 v255, s22, 30
	v_writelane_b32 v255, s23, 31
	v_writelane_b32 v255, s93, 32
	v_writelane_b32 v255, s60, 33
	v_writelane_b32 v255, s92, 34
	s_nop 1
	v_writelane_b32 v255, s93, 35
	s_branch .LBB0_287

; __device__ __forceinline__ void gla_scan_unit(LAS unsigned char* lds, const unsigned char* GPRE, float* GO, int u) {
;     ...
;         const size_t tokc = (size_t)(b * SEQ + ch * 64);
;         bf16x8_t vb[2];
; #pragma unroll
;         for (int ks = 0; ks < 2; ++ks) vb[ks] = *(const LAS bf16x8_t*)(cur + GS_VT + (16 * jt + c) * 144 + (32 * ks + 8 * g) * 2);
;         bf16x8_t sb[3];
; #pragma unroll
;         for (int ks = 0; ks < 3; ++ks) { v4u w; w.x = pk2(S[2 * ks][0], S[2 * ks][1]); w.y = pk2(S[2 * ks][2], S[2 * ks][3]); w.z = pk2(S[2 * ks + 1][0], S[2 * ks + 1][1]); w.w = pk2(S[2 * ks + 1][2], S[2 * ks + 1][3]);
;             sb[ks] = __builtin_bit_cast(bf16x8_t, w); }
; #pragma unroll
;         for (int ti = 0; ti < 2; ++ti) { const int it = 2 * th + ti;
;             f32x4 acc = (f32x4){0.f, 0.f, 0.f, 0.f};
; #pragma unroll
;             for (int ks = 0; ks < 2; ++ks) { const bf16x8_t a = *(const LAS bf16x8_t*)(cur + GS_A + (16 * it + c) * 144 + (32 * ks + 8 * g) * 2);
;                 acc = __builtin_amdgcn_mfma_f32_16x16x32_bf16(a, vb[ks], acc, 0, 0, 0); }
; #pragma unroll
;             for (int ks = 0; ks < 3; ++ks) { const v2u lo = *(const LAS v2u*)(cur + GS_QT + (16 * it + c) * 208 + (32 * ks + 4 * g) * 2), hi = *(const LAS v2u*)(cur + GS_QT + (16 * it + c) * 208 + (32 * ks + 16 + 4 * g) * 2);
;                 const v4u w = (v4u){lo.x, lo.y, hi.x, hi.y};
;                 acc = __builtin_amdgcn_mfma_f32_16x16x32_bf16(__builtin_bit_cast(bf16x8_t, w), sb[ks], acc, 0, 0, 0); }
;             float* op = GO + (tokc + 16 * it + 4 * g) * BRW + h * 192 + 64 * s3 + 16 * jt + c;
;             op[0 * BRW] = acc[0]; op[1 * BRW] = acc[1]; op[2 * BRW] = acc[2]; op[3 * BRW] = acc[3]; }
; #pragma unroll
;         for (int i = 0; i < 6; ++i) { const f32x4 d4 = *(const LAS f32x4*)(cur + GS_DEC + (16 * i + 4 * g) * 4);
;             S[i] = S[i] * d4;
; #pragma unroll
;             for (int ks = 0; ks < 2; ++ks) { const bf16x8_t a = *(const LAS bf16x8_t*)(cur + GS_KST + (16 * i + c) * 144 + (32 * ks + 8 * g) * 2);
;                 S[i] = __builtin_amdgcn_mfma_f32_16x16x32_bf16(a, vb[ks], S[i], 0, 0, 0); } }
;         if (ch + 1 < 32) {
; #pragma unroll
;             for (int i = 0; i < 5; ++i) *(LAS v4u*)(nxt + loff[i]) = rg[i];
;             if (tid < 24) *(LAS v4u*)(nxt + GS_DEC + tid * 16) = rd; }
;         __syncthreads();
;     }
.LBB0_995:
	s_and_b32 s6, 1, s10
	s_cselect_b32 s7, 0, 0xb400
	v_add_u32_e32 v98, s7, v79
	v_add_u32_e32 v99, s7, v83
	v_add_u32_e32 v54, v98, v2
	v_add_u32_e32 v104, v98, v87
	v_add_u32_e32 v110, v98, v95
	v_add_u32_e32 v108, v99, v91
	v_add_u32_e32 v99, v99, v96
	v_add_u32_e32 v146, v98, v97
	ds_read_b128 v[58:61], v54 offset:36352
	ds_read_b128 v[54:57], v54 offset:36416
	ds_read_b128 v[100:103], v104 offset:27136
	ds_read_b128 v[104:107], v104 offset:27200
	ds_read_b128 v[114:117], v110 offset:27200
	ds_read_b128 v[110:113], v110 offset:27136
	ds_read2_b64 v[118:121], v108 offset1:4
	ds_read2_b64 v[130:133], v99 offset1:4
	ds_read2_b64 v[122:125], v108 offset0:8 offset1:12
	ds_read2_b64 v[134:137], v99 offset0:8 offset1:12
	ds_read2_b64 v[126:129], v108 offset0:16 offset1:20
	ds_read2_b64 v[138:141], v99 offset0:16 offset1:20
	ds_read_b128 v[156:159], v98 offset:45568
	ds_read_b128 v[196:199], v146 offset:13312
	ds_read_b128 v[200:203], v146 offset:13376
	v_cvt_pk_bf16_f32 v62, v50, v51
	v_cvt_pk_bf16_f32 v63, v52, v53
	v_cvt_pk_bf16_f32 v64, v42, v43
	v_cvt_pk_bf16_f32 v65, v44, v45
	v_cvt_pk_bf16_f32 v66, v30, v31
	v_cvt_pk_bf16_f32 v67, v32, v33
	v_cvt_pk_bf16_f32 v68, v38, v39
	v_cvt_pk_bf16_f32 v69, v40, v41
	v_cvt_pk_bf16_f32 v70, v34, v35
	v_cvt_pk_bf16_f32 v71, v36, v37
	v_cvt_pk_bf16_f32 v72, v46, v47
	v_cvt_pk_bf16_f32 v73, v48, v49
	s_andn2_b64 vcc, exec, s[4:5]
	s_waitcnt lgkmcnt(12)
	v_mfma_f32_16x16x32_bf16 v[142:145], v[100:103], v[58:61], 0
	s_waitcnt lgkmcnt(9)
	v_mfma_f32_16x16x32_bf16 v[152:155], v[110:113], v[58:61], 0
	v_mfma_f32_16x16x32_bf16 v[142:145], v[104:107], v[54:57], v[142:145]
	v_mfma_f32_16x16x32_bf16 v[152:155], v[114:117], v[54:57], v[152:155]
	ds_read_b128 v[160:163], v98 offset:45632
	ds_read_b128 v[204:207], v146 offset:15616
	ds_read_b128 v[228:231], v146 offset:15680
	ds_read_b128 v[164:167], v98 offset:45696
	ds_read_b128 v[232:235], v146 offset:17920
	ds_read_b128 v[236:239], v146 offset:17984
	s_waitcnt lgkmcnt(14)
	v_mfma_f32_16x16x32_bf16 v[142:145], v[118:121], v[62:65], v[142:145]
	s_waitcnt lgkmcnt(13)
	v_mfma_f32_16x16x32_bf16 v[152:155], v[130:133], v[62:65], v[152:155]
	s_waitcnt lgkmcnt(12)
	v_mfma_f32_16x16x32_bf16 v[142:145], v[122:125], v[66:69], v[142:145]
	s_waitcnt lgkmcnt(11)
	v_mfma_f32_16x16x32_bf16 v[152:155], v[134:137], v[66:69], v[152:155]
	ds_read_b128 v[184:187], v98 offset:45760
	ds_read_b128 v[240:243], v146 offset:20224
	ds_read_b128 v[244:247], v146 offset:20288
	s_waitcnt lgkmcnt(13)
	v_mfma_f32_16x16x32_bf16 v[142:145], v[126:129], v[70:73], v[142:145]
	s_waitcnt lgkmcnt(12)
	v_mfma_f32_16x16x32_bf16 v[152:155], v[138:141], v[70:73], v[152:155]
	s_waitcnt lgkmcnt(11)
	v_pk_mul_f32 v[50:51], v[50:51], v[156:157]
	v_pk_mul_f32 v[52:53], v[52:53], v[158:159]
	s_waitcnt lgkmcnt(8)
	v_pk_mul_f32 v[42:43], v[42:43], v[160:161]
	v_pk_mul_f32 v[44:45], v[44:45], v[162:163]
	v_mfma_f32_16x16x32_bf16 v[50:53], v[196:199], v[58:61], v[50:53]
	v_mfma_f32_16x16x32_bf16 v[50:53], v[200:203], v[54:57], v[50:53]
	ds_read_b128 v[188:191], v98 offset:45824
	ds_read_b128 v[100:103], v146 offset:22528
	ds_read_b128 v[104:107], v146 offset:22592
	ds_read_b128 v[192:195], v98 offset:45888
	ds_read_b128 v[110:113], v146 offset:24832
	ds_read_b128 v[114:117], v146 offset:24896
	s_add_u32 s8, s0, 0x4e200000
	s_addc_u32 s9, s1, 0
	v_lshl_add_u64 v[118:119], v[4:5], 0, s[8:9]
	s_add_u32 s8, s0, 0x4e201000
	s_addc_u32 s9, s1, 0
	v_lshl_add_u64 v[120:121], v[4:5], 0, s[8:9]
	s_add_u32 s8, s0, 0x4e202000
	s_addc_u32 s9, s1, 0
	v_lshl_add_u64 v[122:123], v[4:5], 0, s[8:9]
	s_add_u32 s8, s0, 0x4e20c000
	s_addc_u32 s9, s1, 0
	v_lshl_add_u64 v[124:125], v[4:5], 0, s[8:9]
	s_add_u32 s8, s0, 0x4e20d000
	s_addc_u32 s9, s1, 0
	v_lshl_add_u64 v[126:127], v[4:5], 0, s[8:9]
	s_add_u32 s8, s0, 0x4e20e000
	s_addc_u32 s9, s1, 0
	v_lshl_add_u64 v[128:129], v[4:5], 0, s[8:9]
	global_store_dword v[118:119], v142, off
	global_store_dword v[118:119], v143, off offset:3072
	global_store_dword v[120:121], v144, off offset:2048
	global_store_dword v[122:123], v145, off offset:1024
	s_waitcnt lgkmcnt(11)
	v_pk_mul_f32 v[30:31], v[30:31], v[164:165]
	v_pk_mul_f32 v[32:33], v[32:33], v[166:167]
	v_mfma_f32_16x16x32_bf16 v[42:45], v[204:207], v[58:61], v[42:45]
	v_mfma_f32_16x16x32_bf16 v[42:45], v[228:231], v[54:57], v[42:45]
	global_store_dword v[124:125], v152, off
	global_store_dword v[124:125], v153, off offset:3072
	global_store_dword v[126:127], v154, off offset:2048
	global_store_dword v[128:129], v155, off offset:1024
	s_waitcnt lgkmcnt(8)
	v_pk_mul_f32 v[38:39], v[38:39], v[184:185]
	v_pk_mul_f32 v[40:41], v[40:41], v[186:187]
	v_mfma_f32_16x16x32_bf16 v[30:33], v[232:235], v[58:61], v[30:33]
	v_mfma_f32_16x16x32_bf16 v[30:33], v[236:239], v[54:57], v[30:33]
	s_waitcnt lgkmcnt(5)
	v_pk_mul_f32 v[34:35], v[34:35], v[188:189]
	v_pk_mul_f32 v[36:37], v[36:37], v[190:191]
	v_mfma_f32_16x16x32_bf16 v[38:41], v[240:243], v[58:61], v[38:41]
	v_mfma_f32_16x16x32_bf16 v[38:41], v[244:247], v[54:57], v[38:41]
	s_waitcnt lgkmcnt(2)
	v_pk_mul_f32 v[46:47], v[46:47], v[192:193]
	v_pk_mul_f32 v[48:49], v[48:49], v[194:195]
	v_mfma_f32_16x16x32_bf16 v[34:37], v[100:103], v[58:61], v[34:37]
	v_mfma_f32_16x16x32_bf16 v[34:37], v[104:107], v[54:57], v[34:37]
	s_waitcnt lgkmcnt(1)
	v_mfma_f32_16x16x32_bf16 v[46:49], v[110:113], v[58:61], v[46:49]
	s_waitcnt lgkmcnt(0)
	v_mfma_f32_16x16x32_bf16 v[46:49], v[114:117], v[54:57], v[46:49]
	s_cbranch_vccnz .LBB0_990
	s_cmp_eq_u32 s6, 1
	s_cselect_b32 s4, 0xb400, 0
	s_add_i32 s6, s4, 0
	v_add_u32_e32 v54, s6, v78
	s_waitcnt vmcnt(12)
	ds_write_b128 v54, v[6:9]
	v_add_u32_e32 v54, s6, v82
	s_waitcnt vmcnt(11)
	ds_write_b128 v54, v[10:13]
	v_add_u32_e32 v54, s6, v86
	s_waitcnt vmcnt(10)
	ds_write_b128 v54, v[14:17]
	v_add_u32_e32 v54, s6, v90
	s_waitcnt vmcnt(9)
	ds_write_b128 v54, v[18:21]
	v_add_u32_e32 v54, s6, v94
	s_waitcnt vmcnt(8)
	ds_write_b128 v54, v[26:29]
	s_and_saveexec_b64 s[4:5], s[2:3]
	s_cbranch_execz .LBB0_989
	v_add_u32_e32 v54, s6, v74
	ds_write_b128 v54, v[22:25] offset:45568
	s_branch .LBB0_989
